# rg3: carry chains now run between issuing and consuming the x_r/y_r tile loads (tile-load latency hidden); otherwise as previous
# speedup vs baseline: 1.0048x; 1.0048x over previous
.LBB0_790:
	s_or_b64 exec, exec, s[4:5]
	v_add_u32_e32 v20, s11, v38
	v_add_u32_e32 v22, s11, v39
	v_add_u32_e32 v28, s11, v40
	v_add_u32_e32 v30, s11, v41
	v_ashrrev_i32_e32 v21, 31, v20
	v_ashrrev_i32_e32 v23, 31, v22
	v_ashrrev_i32_e32 v29, 31, v28
	v_ashrrev_i32_e32 v31, 31, v30
	v_lshlrev_b64 v[20:21], 11, v[20:21]
	v_lshlrev_b64 v[22:23], 11, v[22:23]
	v_lshlrev_b64 v[28:29], 11, v[28:29]
	v_lshlrev_b64 v[30:31], 11, v[30:31]
	v_lshl_add_u64 v[20:21], s[0:1], 0, v[20:21]
	v_lshl_add_u64 v[22:23], s[0:1], 0, v[22:23]
	v_lshl_add_u64 v[28:29], s[0:1], 0, v[28:29]
	v_lshl_add_u64 v[30:31], s[0:1], 0, v[30:31]
	v_lshl_add_u64 v[20:21], v[20:21], 0, v[172:173]
	v_lshl_add_u64 v[24:25], v[22:23], 0, v[172:173]
	v_lshl_add_u64 v[28:29], v[28:29], 0, v[172:173]
	v_lshl_add_u64 v[32:33], v[30:31], 0, v[172:173]
	global_load_dwordx4 v[20:23], v[20:21], off offset:1024 nt
	s_nop 0
	global_load_dwordx4 v[24:27], v[24:25], off offset:1024 nt
	s_nop 0
	global_load_dwordx4 v[28:31], v[28:29], off offset:1024 nt
	s_nop 0
	global_load_dwordx4 v[32:35], v[32:33], off offset:1024 nt
	s_mov_b64 s[66:67], vcc
	v_mov_b32_e32 v108, s51
	s_movk_i32 s0, 0xffc0
	s_cmp_gt_i32 s57, 31
	v_bfi_b32 v108, s0, v108, v36
	s_cselect_b64 s[68:69], -1, 0
	s_mov_b64 s[0:1], -1
	s_and_b64 vcc, exec, s[68:69]
	v_ashrrev_i32_e32 v109, 31, v108
	s_cbranch_vccnz .LBB0_798
	s_mov_b64 s[0:1], 0
.LBB0_798:
	v_mov_b32_e32 v115, 0
	s_andn2_b64 vcc, exec, s[0:1]
	v_mov_b32_e32 v113, 0
	s_cbranch_vccnz .LBB0_800
	s_load_dwordx2 s[0:1], s[64:65], 0x10
	s_lshl_b32 s4, s57, 1
	s_add_i32 s26, s4, s8
	s_lshl_b64 s[4:5], s[26:27], 12
	s_waitcnt lgkmcnt(0)
	s_add_u32 s0, s0, s4
	s_addc_u32 s1, s1, s5
	v_lshl_add_u64 v[110:111], v[108:109], 2, s[0:1]
	global_load_dword v113, v[110:111], off
	global_load_dword v115, v[110:111], off offset:2048
.LBB0_800:
	s_and_b32 s0, s28, s13
	s_add_u32 s72, s62, 0x432000
	s_addc_u32 s73, s63, 0
	v_lshlrev_b32_e32 v110, 3, v108
	s_lshl_b32 s4, s0, 13
	s_add_u32 s94, s72, s4
	s_addc_u32 s95, s73, 0
	s_movk_i32 s96, 0x2000
	s_mov_b32 s97, 0
	s_mov_b32 s92, s71
	s_mov_b32 s98, 0

.Lcarry_loads:
	global_load_dwordx2 v[44:45], v110, s[94:95]
	s_add_u32 s94, s94, s96
	s_addc_u32 s95, s95, s97
	s_cmp_le_u32 s92, 1
	s_cbranch_scc1 .Lcarry_issued
	global_load_dwordx2 v[46:47], v110, s[94:95]
	s_add_u32 s94, s94, s96
	s_addc_u32 s95, s95, s97
	s_cmp_le_u32 s92, 2
	s_cbranch_scc1 .Lcarry_issued
	global_load_dwordx2 v[48:49], v110, s[94:95]
	s_add_u32 s94, s94, s96
	s_addc_u32 s95, s95, s97
	s_cmp_le_u32 s92, 3
	s_cbranch_scc1 .Lcarry_issued
	global_load_dwordx2 v[50:51], v110, s[94:95]
	s_add_u32 s94, s94, s96
	s_addc_u32 s95, s95, s97
	s_cmp_le_u32 s92, 4
	s_cbranch_scc1 .Lcarry_issued
	global_load_dwordx2 v[52:53], v110, s[94:95]
	s_add_u32 s94, s94, s96
	s_addc_u32 s95, s95, s97
	s_cmp_le_u32 s92, 5
	s_cbranch_scc1 .Lcarry_issued
	global_load_dwordx2 v[54:55], v110, s[94:95]
	s_add_u32 s94, s94, s96
	s_addc_u32 s95, s95, s97
	s_cmp_le_u32 s92, 6
	s_cbranch_scc1 .Lcarry_issued
	global_load_dwordx2 v[56:57], v110, s[94:95]
	s_add_u32 s94, s94, s96
	s_addc_u32 s95, s95, s97
	s_cmp_le_u32 s92, 7
	s_cbranch_scc1 .Lcarry_issued
	global_load_dwordx2 v[58:59], v110, s[94:95]
	s_add_u32 s94, s94, s96
	s_addc_u32 s95, s95, s97
	s_cmp_le_u32 s92, 8
	s_cbranch_scc1 .Lcarry_issued
	global_load_dwordx2 v[60:61], v110, s[94:95]
	s_add_u32 s94, s94, s96
	s_addc_u32 s95, s95, s97
	s_cmp_le_u32 s92, 9
	s_cbranch_scc1 .Lcarry_issued
	global_load_dwordx2 v[62:63], v110, s[94:95]
	s_add_u32 s94, s94, s96
	s_addc_u32 s95, s95, s97
	s_cmp_le_u32 s92, 10
	s_cbranch_scc1 .Lcarry_issued
	global_load_dwordx2 v[64:65], v110, s[94:95]
	s_add_u32 s94, s94, s96
	s_addc_u32 s95, s95, s97
	s_cmp_le_u32 s92, 11
	s_cbranch_scc1 .Lcarry_issued
	global_load_dwordx2 v[66:67], v110, s[94:95]
	s_add_u32 s94, s94, s96
	s_addc_u32 s95, s95, s97
	s_cmp_le_u32 s92, 12
	s_cbranch_scc1 .Lcarry_issued
	global_load_dwordx2 v[68:69], v110, s[94:95]
	s_add_u32 s94, s94, s96
	s_addc_u32 s95, s95, s97
	s_cmp_le_u32 s92, 13
	s_cbranch_scc1 .Lcarry_issued
	global_load_dwordx2 v[70:71], v110, s[94:95]
	s_add_u32 s94, s94, s96
	s_addc_u32 s95, s95, s97
	s_cmp_le_u32 s92, 14
	s_cbranch_scc1 .Lcarry_issued
	global_load_dwordx2 v[72:73], v110, s[94:95]
	s_add_u32 s94, s94, s96
	s_addc_u32 s95, s95, s97
	s_cmp_le_u32 s92, 15
	s_cbranch_scc1 .Lcarry_issued
	global_load_dwordx2 v[74:75], v110, s[94:95]
	s_add_u32 s94, s94, s96
	s_addc_u32 s95, s95, s97
	s_cmp_le_u32 s92, 16
	s_cbranch_scc1 .Lcarry_issued
	global_load_dwordx2 v[76:77], v110, s[94:95]
	s_add_u32 s94, s94, s96
	s_addc_u32 s95, s95, s97
	s_cmp_le_u32 s92, 17
	s_cbranch_scc1 .Lcarry_issued
	global_load_dwordx2 v[78:79], v110, s[94:95]
	s_add_u32 s94, s94, s96
	s_addc_u32 s95, s95, s97
	s_cmp_le_u32 s92, 18
	s_cbranch_scc1 .Lcarry_issued
	global_load_dwordx2 v[80:81], v110, s[94:95]
	s_add_u32 s94, s94, s96
	s_addc_u32 s95, s95, s97
	s_cmp_le_u32 s92, 19
	s_cbranch_scc1 .Lcarry_issued
	global_load_dwordx2 v[82:83], v110, s[94:95]
	s_add_u32 s94, s94, s96
	s_addc_u32 s95, s95, s97
	s_cmp_le_u32 s92, 20
	s_cbranch_scc1 .Lcarry_issued
	global_load_dwordx2 v[84:85], v110, s[94:95]
	s_add_u32 s94, s94, s96
	s_addc_u32 s95, s95, s97
	s_cmp_le_u32 s92, 21
	s_cbranch_scc1 .Lcarry_issued
	global_load_dwordx2 v[86:87], v110, s[94:95]
	s_add_u32 s94, s94, s96
	s_addc_u32 s95, s95, s97
	s_cmp_le_u32 s92, 22
	s_cbranch_scc1 .Lcarry_issued
	global_load_dwordx2 v[88:89], v110, s[94:95]
	s_add_u32 s94, s94, s96
	s_addc_u32 s95, s95, s97
	s_cmp_le_u32 s92, 23
	s_cbranch_scc1 .Lcarry_issued
	global_load_dwordx2 v[90:91], v110, s[94:95]
	s_add_u32 s94, s94, s96
	s_addc_u32 s95, s95, s97
	s_cmp_le_u32 s92, 24
	s_cbranch_scc1 .Lcarry_issued
	global_load_dwordx2 v[92:93], v110, s[94:95]
	s_add_u32 s94, s94, s96
	s_addc_u32 s95, s95, s97
	s_cmp_le_u32 s92, 25
	s_cbranch_scc1 .Lcarry_issued
	global_load_dwordx2 v[94:95], v110, s[94:95]
	s_add_u32 s94, s94, s96
	s_addc_u32 s95, s95, s97
	s_cmp_le_u32 s92, 26
	s_cbranch_scc1 .Lcarry_issued
	global_load_dwordx2 v[96:97], v110, s[94:95]
	s_add_u32 s94, s94, s96
	s_addc_u32 s95, s95, s97
	s_cmp_le_u32 s92, 27
	s_cbranch_scc1 .Lcarry_issued
	global_load_dwordx2 v[98:99], v110, s[94:95]
	s_add_u32 s94, s94, s96
	s_addc_u32 s95, s95, s97
	s_cmp_le_u32 s92, 28
	s_cbranch_scc1 .Lcarry_issued
	global_load_dwordx2 v[100:101], v110, s[94:95]
	s_add_u32 s94, s94, s96
	s_addc_u32 s95, s95, s97
	s_cmp_le_u32 s92, 29
	s_cbranch_scc1 .Lcarry_issued
	global_load_dwordx2 v[102:103], v110, s[94:95]
	s_add_u32 s94, s94, s96
	s_addc_u32 s95, s95, s97
	s_cmp_le_u32 s92, 30
	s_cbranch_scc1 .Lcarry_issued
	global_load_dwordx2 v[104:105], v110, s[94:95]
	s_add_u32 s94, s94, s96
	s_addc_u32 s95, s95, s97
	s_cmp_le_u32 s92, 31
	s_cbranch_scc1 .Lcarry_issued
	global_load_dwordx2 v[106:107], v110, s[94:95]
	s_add_u32 s94, s94, s96
	s_addc_u32 s95, s95, s97

.Lcarry_chain_done:
	s_cmp_lg_u32 s98, 0
	s_cbranch_scc1 .Lcarry_all_done
	s_waitcnt vmcnt(0)
	v_swap_b32 v113, v115
	s_mov_b32 s98, 1
	s_sub_u32 s92, s70, s71
	s_add_u32 s4, s0, s70
	s_lshl_b32 s4, s4, 13
	s_add_u32 s94, s72, s4
	s_addc_u32 s95, s73, 0
	s_add_u32 s94, s94, 0x1000
	s_addc_u32 s95, s95, 0
	s_mov_b32 s96, 0xffffe000
	s_mov_b32 s97, -1
	s_branch .Lcarry_chain
.Lcarry_all_done:
	v_swap_b32 v113, v115
	s_and_b32 s28, s51, 0xffffffc0
	v_and_b32_e32 v112, 63, v36
	s_mov_b64 vcc, s[66:67]
	v_add_u32_e32 v43, 0, v172
	s_and_saveexec_b64 s[0:1], vcc
	s_cbranch_execz .LBB0_812
	v_lshl_add_u32 v38, v38, 10, v43
	s_waitcnt vmcnt(4)
	ds_write_b128 v38, v[4:7]
	s_or_b64 exec, exec, s[0:1]
	s_and_saveexec_b64 s[0:1], s[40:41]
	s_cbranch_execnz .LBB0_813

.LBB0_796:
	s_or_b64 exec, exec, s[0:1]
	s_waitcnt vmcnt(4)
	v_and_b32_e32 v0, 0x7ffffe00, v37
	v_lshl_add_u32 v0, v0, 1, v43
	s_waitcnt vmcnt(3)
	ds_write_b128 v0, v[20:23] offset:35840
	s_waitcnt vmcnt(2)
	ds_write_b128 v0, v[24:27] offset:44032
	s_waitcnt vmcnt(1)
	ds_write_b128 v0, v[28:31] offset:52224
	s_waitcnt vmcnt(0)
	ds_write_b128 v0, v[32:35] offset:60416
	v_mov_b32_e32 v0, v108
	v_mov_b32_e32 v1, v109
	s_cmp_eq_u32 s71, 0
	s_cselect_b64 s[44:45], -1, 0
	s_branch .LBB0_819
